# v37 + HGRN merge (mg_head): 16-lane RMS reduction by DPP adds instead of four ds_bpermute round trips
# speedup vs baseline: 1.0002x; 1.0002x over previous
.LBB0_703:
	v_lshl_add_u64 v[18:19], s[78:79], 0, v[8:9]
	v_add_co_u32_e32 v14, vcc, 0x25c00000, v18
	v_lshl_add_u64 v[20:21], v[18:19], 0, s[52:53]
	s_nop 0
	v_addc_co_u32_e32 v15, vcc, 0, v19, vcc
	v_lshl_add_u64 v[28:29], v[18:19], 0, s[70:71]
	v_add_co_u32_e32 v18, vcc, 0x27400000, v18
	global_load_dwordx4 v[14:17], v[14:15], off
	s_nop 0
	global_load_dwordx4 v[24:27], v[20:21], off offset:16
	v_addc_co_u32_e32 v19, vcc, 0, v19, vcc
	global_load_dwordx4 v[18:21], v[18:19], off
	s_nop 0
	global_load_dwordx4 v[28:31], v[28:29], off offset:16
	v_lshl_add_u64 v[8:9], v[8:9], 0, s[74:75]
	s_waitcnt vmcnt(1)
	v_pk_add_f32 v[16:17], v[16:17], v[20:21]
	v_pk_add_f32 v[20:21], v[14:15], v[18:19]
	s_waitcnt vmcnt(0)
	v_pk_add_f32 v[14:15], v[26:27], v[30:31]
	v_pk_add_f32 v[18:19], v[24:25], v[28:29]
	v_pk_mul_f32 v[24:25], v[16:17], v[16:17]
	v_pk_mul_f32 v[26:27], v[20:21], v[20:21]
	s_nop 0
	v_pk_mov_b32 v[28:29], v[26:27], v[24:25] op_sel:[1,0]
	v_mov_b32_e32 v27, v25
	v_pk_add_f32 v[24:25], v[28:29], v[26:27]
	v_pk_mul_f32 v[26:27], v[14:15], v[14:15]
	v_pk_mul_f32 v[28:29], v[18:19], v[18:19]
	v_mov_b32_e32 v30, v26
	v_mov_b32_e32 v31, v28
	v_mov_b32_e32 v28, v27
	v_pk_add_f32 v[26:27], v[30:31], v[28:29]
	v_add_f32_e32 v22, v24, v25
	v_add_f32_e32 v22, v22, v27
	v_add_f32_e32 v22, v26, v22
	s_nop 1
	v_add_f32_dpp v22, v22, v22 quad_perm:[1,0,3,2] row_mask:0xf bank_mask:0xf
	s_nop 1
	v_add_f32_dpp v22, v22, v22 quad_perm:[2,3,0,1] row_mask:0xf bank_mask:0xf
	s_nop 1
	v_add_f32_dpp v22, v22, v22 row_half_mirror row_mask:0xf bank_mask:0xf
	s_nop 1
	v_add_f32_dpp v22, v22, v22 row_mirror row_mask:0xf bank_mask:0xf
	s_nop 0
	v_fmamk_f32 v22, v22, 0x3c000000, v218
	v_cmp_gt_f32_e32 vcc, s77, v22
	v_mul_f32_e32 v24, 0x4f800000, v22
	s_nop 0
	v_cndmask_b32_e32 v22, v22, v24, vcc
	v_sqrt_f32_e32 v24, v22
	s_nop 0
	v_add_u32_e32 v25, -1, v24
	v_fma_f32 v26, -v25, v24, v22
	v_cmp_ge_f32_e64 s[40:41], 0, v26
	v_add_u32_e32 v26, 1, v24
	s_nop 0
	v_cndmask_b32_e64 v25, v24, v25, s[40:41]
	v_fma_f32 v24, -v26, v24, v22
	v_cmp_lt_f32_e64 s[40:41], 0, v24
	s_nop 1
	v_cndmask_b32_e64 v24, v25, v26, s[40:41]
	v_mul_f32_e32 v25, 0x37800000, v24
	v_cndmask_b32_e32 v24, v24, v25, vcc
	v_cmp_class_f32_e32 vcc, v22, v219
	s_nop 1
	v_cndmask_b32_e32 v22, v24, v22, vcc
	v_div_scale_f32 v24, s[12:13], v22, v22, 1.0
	v_rcp_f32_e32 v25, v24
	s_nop 0
	v_fma_f32 v26, -v24, v25, 1.0
	v_fmac_f32_e32 v25, v26, v25
	v_div_scale_f32 v26, vcc, 1.0, v22, 1.0
	v_mul_f32_e32 v27, v26, v25
	v_fma_f32 v28, -v24, v27, v26
	v_fmac_f32_e32 v27, v28, v25
	v_fma_f32 v24, -v24, v27, v26
	v_div_fmas_f32 v24, v24, v25, v27
	v_div_fixup_f32 v22, v24, v22, 1.0
	v_lshl_add_u64 v[24:25], s[78:79], 0, v[10:11]
	global_load_dwordx4 v[24:27], v[24:25], off
	v_pk_mul_f32 v[20:21], v[20:21], v[22:23] op_sel_hi:[1,0]
	v_pk_mul_f32 v[16:17], v[16:17], v[22:23] op_sel_hi:[1,0]
	v_pk_mul_f32 v[20:21], v[0:1], v[20:21]
	v_pk_mul_f32 v[18:19], v[18:19], v[22:23] op_sel_hi:[1,0]
	v_pk_mul_f32 v[16:17], v[2:3], v[16:17]
	v_pk_mul_f32 v[14:15], v[14:15], v[22:23] op_sel_hi:[1,0]
	v_pk_mul_f32 v[18:19], v[4:5], v[18:19]
	v_pk_mul_f32 v[14:15], v[6:7], v[14:15]
	v_add_u32_e32 v23, 32, v23
	v_cmp_le_i32_e32 vcc, s81, v23
	v_lshl_add_u64 v[10:11], v[10:11], 0, s[68:69]
	s_or_b64 s[8:9], vcc, s[8:9]
	s_waitcnt vmcnt(0)
	v_lshlrev_b32_e32 v28, 16, v24
	v_and_b32_e32 v29, 0xffff0000, v24
	v_lshlrev_b32_e32 v24, 16, v25
	v_and_b32_e32 v25, 0xffff0000, v25
	v_pk_mul_f32 v[20:21], v[20:21], v[28:29]
	v_lshlrev_b32_e32 v28, 16, v26
	v_and_b32_e32 v29, 0xffff0000, v26
	v_pk_mul_f32 v[16:17], v[16:17], v[24:25]
	v_lshlrev_b32_e32 v24, 16, v27
	v_and_b32_e32 v25, 0xffff0000, v27
	v_pk_mul_f32 v[18:19], v[18:19], v[28:29]
	v_pk_mul_f32 v[24:25], v[14:15], v[24:25]
	v_cvt_pk_bf16_f32 v14, v20, v21
	v_cvt_pk_bf16_f32 v15, v16, v17
	v_cvt_pk_bf16_f32 v16, v18, v19
	v_cvt_pk_bf16_f32 v17, v24, v25
	v_lshl_add_u64 v[18:19], s[78:79], 0, v[12:13]
	v_lshl_add_u64 v[12:13], v[12:13], 0, s[30:31]
	global_store_dwordx4 v[18:19], v[14:17], off
	s_andn2_b64 exec, exec, s[8:9]
	s_cbranch_execnz .LBB0_703

.LBB0_827:
	v_lshl_add_u64 v[18:19], s[78:79], 0, v[8:9]
	v_add_co_u32_e32 v14, vcc, 0x25c00000, v18
	v_lshl_add_u64 v[20:21], v[18:19], 0, s[52:53]
	s_nop 0
	v_addc_co_u32_e32 v15, vcc, 0, v19, vcc
	v_lshl_add_u64 v[28:29], v[18:19], 0, s[70:71]
	v_add_co_u32_e32 v18, vcc, 0x27400000, v18
	global_load_dwordx4 v[14:17], v[14:15], off
	s_nop 0
	global_load_dwordx4 v[24:27], v[20:21], off offset:16
	v_addc_co_u32_e32 v19, vcc, 0, v19, vcc
	global_load_dwordx4 v[18:21], v[18:19], off
	s_nop 0
	global_load_dwordx4 v[28:31], v[28:29], off offset:16
	v_lshl_add_u64 v[8:9], v[8:9], 0, s[74:75]
	s_waitcnt vmcnt(1)
	v_pk_add_f32 v[16:17], v[16:17], v[20:21]
	v_pk_add_f32 v[20:21], v[14:15], v[18:19]
	s_waitcnt vmcnt(0)
	v_pk_add_f32 v[14:15], v[26:27], v[30:31]
	v_pk_add_f32 v[18:19], v[24:25], v[28:29]
	v_pk_mul_f32 v[24:25], v[16:17], v[16:17]
	v_pk_mul_f32 v[26:27], v[20:21], v[20:21]
	s_nop 0
	v_pk_mov_b32 v[28:29], v[26:27], v[24:25] op_sel:[1,0]
	v_mov_b32_e32 v27, v25
	v_pk_add_f32 v[24:25], v[28:29], v[26:27]
	v_pk_mul_f32 v[26:27], v[14:15], v[14:15]
	v_pk_mul_f32 v[28:29], v[18:19], v[18:19]
	v_mov_b32_e32 v30, v26
	v_mov_b32_e32 v31, v28
	v_mov_b32_e32 v28, v27
	v_pk_add_f32 v[26:27], v[30:31], v[28:29]
	v_add_f32_e32 v22, v24, v25
	v_add_f32_e32 v22, v22, v27
	v_add_f32_e32 v22, v26, v22
	s_nop 1
	v_add_f32_dpp v22, v22, v22 quad_perm:[1,0,3,2] row_mask:0xf bank_mask:0xf
	s_nop 1
	v_add_f32_dpp v22, v22, v22 quad_perm:[2,3,0,1] row_mask:0xf bank_mask:0xf
	s_nop 1
	v_add_f32_dpp v22, v22, v22 row_half_mirror row_mask:0xf bank_mask:0xf
	s_nop 1
	v_add_f32_dpp v22, v22, v22 row_mirror row_mask:0xf bank_mask:0xf
	s_nop 0
	v_fmamk_f32 v22, v22, 0x3c000000, v218
	v_cmp_gt_f32_e32 vcc, s77, v22
	v_mul_f32_e32 v24, 0x4f800000, v22
	s_nop 0
	v_cndmask_b32_e32 v22, v22, v24, vcc
	v_sqrt_f32_e32 v24, v22
	s_nop 0
	v_add_u32_e32 v25, -1, v24
	v_fma_f32 v26, -v25, v24, v22
	v_cmp_ge_f32_e64 s[40:41], 0, v26
	v_add_u32_e32 v26, 1, v24
	s_nop 0
	v_cndmask_b32_e64 v25, v24, v25, s[40:41]
	v_fma_f32 v24, -v26, v24, v22
	v_cmp_lt_f32_e64 s[40:41], 0, v24
	s_nop 1
	v_cndmask_b32_e64 v24, v25, v26, s[40:41]
	v_mul_f32_e32 v25, 0x37800000, v24
	v_cndmask_b32_e32 v24, v24, v25, vcc
	v_cmp_class_f32_e32 vcc, v22, v219
	s_nop 1
	v_cndmask_b32_e32 v22, v24, v22, vcc
	v_div_scale_f32 v24, s[8:9], v22, v22, 1.0
	v_rcp_f32_e32 v25, v24
	s_nop 0
	v_fma_f32 v26, -v24, v25, 1.0
	v_fmac_f32_e32 v25, v26, v25
	v_div_scale_f32 v26, vcc, 1.0, v22, 1.0
	v_mul_f32_e32 v27, v26, v25
	v_fma_f32 v28, -v24, v27, v26
	v_fmac_f32_e32 v27, v28, v25
	v_fma_f32 v24, -v24, v27, v26
	v_div_fmas_f32 v24, v24, v25, v27
	v_div_fixup_f32 v22, v24, v22, 1.0
	v_lshl_add_u64 v[24:25], s[78:79], 0, v[10:11]
	global_load_dwordx4 v[24:27], v[24:25], off
	v_pk_mul_f32 v[20:21], v[20:21], v[22:23] op_sel_hi:[1,0]
	v_pk_mul_f32 v[16:17], v[16:17], v[22:23] op_sel_hi:[1,0]
	v_pk_mul_f32 v[20:21], v[0:1], v[20:21]
	v_pk_mul_f32 v[18:19], v[18:19], v[22:23] op_sel_hi:[1,0]
	v_pk_mul_f32 v[16:17], v[2:3], v[16:17]
	v_pk_mul_f32 v[14:15], v[14:15], v[22:23] op_sel_hi:[1,0]
	v_pk_mul_f32 v[18:19], v[4:5], v[18:19]
	v_pk_mul_f32 v[14:15], v[6:7], v[14:15]
	v_add_u32_e32 v23, 32, v23
	v_cmp_le_i32_e32 vcc, s54, v23
	v_lshl_add_u64 v[10:11], v[10:11], 0, s[68:69]
	s_or_b64 s[6:7], vcc, s[6:7]
	s_waitcnt vmcnt(0)
	v_lshlrev_b32_e32 v28, 16, v24
	v_and_b32_e32 v29, 0xffff0000, v24
	v_lshlrev_b32_e32 v24, 16, v25
	v_and_b32_e32 v25, 0xffff0000, v25
	v_pk_mul_f32 v[20:21], v[20:21], v[28:29]
	v_lshlrev_b32_e32 v28, 16, v26
	v_and_b32_e32 v29, 0xffff0000, v26
	v_pk_mul_f32 v[16:17], v[16:17], v[24:25]
	v_lshlrev_b32_e32 v24, 16, v27
	v_and_b32_e32 v25, 0xffff0000, v27
	v_pk_mul_f32 v[18:19], v[18:19], v[28:29]
	v_pk_mul_f32 v[24:25], v[14:15], v[24:25]
	v_cvt_pk_bf16_f32 v14, v20, v21
	v_cvt_pk_bf16_f32 v15, v16, v17
	v_cvt_pk_bf16_f32 v16, v18, v19
	v_cvt_pk_bf16_f32 v17, v24, v25
	v_lshl_add_u64 v[18:19], s[78:79], 0, v[12:13]
	v_lshl_add_u64 v[12:13], v[12:13], 0, s[30:31]
	global_store_dwordx4 v[18:19], v[14:17], off
	s_andn2_b64 exec, exec, s[6:7]
	s_cbranch_execnz .LBB0_827
	s_branch .LBB0_651
